# speedup vs baseline: 1.0096x; 1.0096x over previous
; __device__ void phaseA1(const Params& p) {
;     ...
;     #pragma unroll
;     for (int nb = 0; nb < 2; ++nb) {
;       const int cl = q * 32 + nb * 16 + fr;
;       float* hdst = reinterpret_cast<float*>(sm + (dir == 0 ? SC_HF : SC_HB));
;       u16* pdst = reinterpret_cast<u16*>(sm + (dir == 0 ? SC_PF : SC_PB));
;       #pragma unroll
;       for (int m = 0; m < 4; ++m)
;         #pragma unroll
;         for (int j = 0; j < 4; ++j) {
;           const int tt = m * 16 + fq * 4 + j;
;           hdst[tt * 132 + cl] = v2[nb][m][j];
;           pdst[tt * 136 + cl] = (u16)f2bf(a2[nb][m][j]);
;         }
;     }
;     __syncthreads();
.LBB0_438:
	s_or_b64 exec, exec, s[76:77]
	v_bfe_u32 v77, v109, 16, 1
	v_add3_u32 v77, v109, v77, s84
	v_bfe_u32 v78, v108, 16, 1
	s_barrier
	v_add_u32_e32 v76, v220, v216
	ds_write_b16_d16_hi v233, v77
	v_add_u32_e32 v77, v220, v217
	v_add3_u32 v78, v108, v78, s84
	ds_write_b32 v76, v113
	ds_write_b32 v77, v112
	ds_write_b16_d16_hi v234, v78
	ds_write_b32 v77, v119 offset:528
	v_bfe_u32 v78, v111, 16, 1
	v_add3_u32 v78, v111, v78, s84
	ds_write_b16_d16_hi v234, v78 offset:272
	ds_write_b32 v77, v118 offset:1056
	v_bfe_u32 v78, v110, 16, 1
	v_add3_u32 v78, v110, v78, s84
	ds_write_b16_d16_hi v234, v78 offset:544
	ds_write_b32 v77, v121 offset:7920
	v_bfe_u32 v78, v117, 16, 1
	v_add3_u32 v78, v117, v78, s84
	ds_write_b16_d16_hi v234, v78 offset:4080
	ds_write_b32 v77, v120 offset:8448
	v_bfe_u32 v78, v116, 16, 1
	v_add3_u32 v78, v116, v78, s84
	ds_write_b16_d16_hi v234, v78 offset:4352
	ds_write_b32 v77, v123 offset:8976
	v_bfe_u32 v78, v115, 16, 1
	v_add3_u32 v78, v115, v78, s84
	v_bfe_u32 v79, v114, 16, 1
	ds_write_b16_d16_hi v234, v78 offset:4624
	v_add_u32_e32 v78, v220, v218
	v_add3_u32 v79, v114, v79, s84
	ds_write_b32 v78, v122 offset:528
	ds_write_b16_d16_hi v234, v79 offset:4896
	ds_write_b32 v78, v151 offset:7392
	v_bfe_u32 v79, v143, 16, 1
	v_add3_u32 v79, v143, v79, s84
	ds_write_b16_d16_hi v234, v79 offset:8432
	ds_write_b32 v78, v150 offset:7920
	v_bfe_u32 v79, v142, 16, 1
	v_add3_u32 v79, v142, v79, s84
	ds_write_b16_d16_hi v234, v79 offset:8704
	ds_write_b32 v78, v155 offset:8448
	v_bfe_u32 v79, v145, 16, 1
	v_add3_u32 v79, v145, v79, s84
	ds_write_b16_d16_hi v234, v79 offset:8976
	ds_write_b32 v78, v154 offset:8976
	v_bfe_u32 v79, v144, 16, 1
	v_add3_u32 v79, v144, v79, s84
	ds_write_b16_d16_hi v234, v79 offset:9248
	ds_write_b32 v78, v153 offset:15840
	v_bfe_u32 v79, v147, 16, 1
	v_add3_u32 v79, v147, v79, s84
	ds_write_b16_d16_hi v234, v79 offset:12784
	ds_write_b32 v78, v152 offset:16368
	v_bfe_u32 v79, v146, 16, 1
	v_add3_u32 v79, v146, v79, s84
	ds_write_b16_d16_hi v234, v79 offset:13056
	ds_write_b32 v78, v157 offset:16896
	v_bfe_u32 v79, v149, 16, 1
	v_add3_u32 v79, v149, v79, s84
	ds_write_b16_d16_hi v234, v79 offset:13328
	ds_write_b32 v78, v156 offset:17424
	v_bfe_u32 v79, v148, 16, 1
	v_add3_u32 v79, v148, v79, s84
	ds_write_b16_d16_hi v234, v79 offset:13600
	ds_write_b32 v76, v163 offset:64
	v_bfe_u32 v76, v81, 16, 1
	v_add3_u32 v76, v81, v76, s84
	ds_write_b16_d16_hi v233, v76 offset:32
	ds_write_b32 v77, v162 offset:64
	v_bfe_u32 v76, v80, 16, 1
	v_add3_u32 v76, v80, v76, s84
	ds_write_b16_d16_hi v234, v76 offset:32
	ds_write_b32 v77, v169 offset:592
	v_bfe_u32 v76, v83, 16, 1
	v_add3_u32 v76, v83, v76, s84
	ds_write_b16_d16_hi v234, v76 offset:304
	ds_write_b32 v77, v168 offset:1120
	v_bfe_u32 v76, v82, 16, 1
	v_add3_u32 v76, v82, v76, s84
	ds_write_b16_d16_hi v234, v76 offset:576
	ds_write_b32 v77, v171 offset:7984
	v_bfe_u32 v76, v165, 16, 1
	v_add3_u32 v76, v165, v76, s84
	ds_write_b16_d16_hi v234, v76 offset:4112
	ds_write_b32 v77, v170 offset:8512
	v_bfe_u32 v76, v164, 16, 1
	v_add3_u32 v76, v164, v76, s84
	ds_write_b16_d16_hi v234, v76 offset:4384
	ds_write_b32 v78, v173 offset:64
	v_bfe_u32 v76, v167, 16, 1
	v_add3_u32 v76, v167, v76, s84
	ds_write_b16_d16_hi v234, v76 offset:4656
	ds_write_b32 v78, v172 offset:592
	v_bfe_u32 v76, v166, 16, 1
	v_add3_u32 v76, v166, v76, s84
	ds_write_b16_d16_hi v234, v76 offset:4928
	ds_write_b32 v78, v183 offset:7456
	v_bfe_u32 v76, v175, 16, 1
	v_add3_u32 v76, v175, v76, s84
	ds_write_b16_d16_hi v234, v76 offset:8464
	ds_write_b32 v78, v182 offset:7984
	v_bfe_u32 v76, v174, 16, 1
	v_add3_u32 v76, v174, v76, s84
	ds_write_b16_d16_hi v234, v76 offset:8736
	ds_write_b32 v78, v187 offset:8512
	v_bfe_u32 v76, v177, 16, 1
	v_add3_u32 v76, v177, v76, s84
	ds_write_b16_d16_hi v234, v76 offset:9008
	ds_write_b32 v78, v186 offset:9040
	v_bfe_u32 v76, v176, 16, 1
	v_add3_u32 v76, v176, v76, s84
	ds_write_b16_d16_hi v234, v76 offset:9280
	ds_write_b32 v78, v185 offset:15904
	v_bfe_u32 v76, v179, 16, 1
	v_add3_u32 v76, v179, v76, s84
	ds_write_b16_d16_hi v234, v76 offset:12816
	ds_write_b32 v78, v184 offset:16432
	v_bfe_u32 v76, v178, 16, 1
	v_add3_u32 v76, v178, v76, s84
	ds_write_b16_d16_hi v234, v76 offset:13088
	ds_write_b32 v78, v189 offset:16960
	v_bfe_u32 v76, v181, 16, 1
	v_add3_u32 v76, v181, v76, s84
	ds_write_b16_d16_hi v234, v76 offset:13360
	ds_write_b32 v78, v188 offset:17488
	v_bfe_u32 v76, v180, 16, 1
	v_add3_u32 v76, v180, v76, s84
	ds_write_b16_d16_hi v234, v76 offset:13632
	v_mov_b32_e32 v76, v194
	s_waitcnt lgkmcnt(0)
	s_barrier
; __device__ __forceinline__ int otid() { int t = threadIdx.x; asm volatile("" : "+v"(t)); return t; }
; __device__ void phaseA1(const Params& p) {
;     ...
;     {
;       const float* hf = reinterpret_cast<const float*>(sm + SC_HF);
;       const float* hb = reinterpret_cast<const float*>(sm + SC_HB);
;       const int tq = otid();
;       const int ctt = tq >> 3, ccl = (tq & 7) * 4;
;       const int tok = t0 + ctt;
;       unsigned char* Pf8 = (unsigned char*)p.out + OUT_OFF_TP;
;       unsigned char* Pb8 = (unsigned char*)(ws + OFF_ZB);
;       #pragma unroll
;       for (int sub = 0; sub < 4; ++sub) {
;         const int cl = ccl + sub * 32;
;         const size_t gi = (size_t)tok * D + h * 128 + cl;
;         const float4 f = *reinterpret_cast<const float4*>(hf + ctt * 132 + cl);
;         const float4 g = *reinterpret_cast<const float4*>(hb + ctt * 132 + cl);
;         v2u o;
;         o.x = pk2(f.x + g.x, f.y + g.y);
;         o.y = pk2(f.z + g.z, f.w + g.w);
;         *reinterpret_cast<v2u*>(Sarr + gi) = o;
;         const v2u pfv = *reinterpret_cast<const v2u*>(sm + SC_PF + ctt * 272 + cl * 2);
;         const v2u pbv = *reinterpret_cast<const v2u*>(sm + SC_PB + ctt * 272 + cl * 2);
;         *reinterpret_cast<unsigned*>(Pf8 + gi) = pk4_u8(bflo(pfv.x), bfhi(pfv.x), bflo(pfv.y), bfhi(pfv.y));
;         *reinterpret_cast<unsigned*>(Pb8 + gi) = pk4_u8(bflo(pbv.x), bfhi(pbv.x), bflo(pbv.y), bfhi(pbv.y));
;       }
	s_lshl_b32 s24, s91, 7
	v_lshrrev_b32_e32 v112, 3, v194
	v_and_b32_e32 v113, 7, v194
	v_lshlrev_b32_e32 v113, 4, v113
	v_mul_u32_u24_e32 v76, 0x210, v112
	v_lshl_add_u32 v76, v113, 2, v76
	v_add_u32_e32 v77, 0x14c00, v76
	v_mul_u32_u24_e32 v78, 0x110, v112
	v_lshl_add_u32 v78, v113, 1, v78
	ds_read_b128 v[80:83], v76 offset:51200
	ds_read_b128 v[84:87], v76 offset:51216
	ds_read_b128 v[88:91], v76 offset:51232
	ds_read_b128 v[92:95], v76 offset:51248
	ds_read_b128 v[96:99], v77
	ds_read_b128 v[100:103], v77 offset:16
	ds_read_b128 v[150:153], v77 offset:32
	ds_read_b128 v[154:157], v77 offset:48
	ds_read_b128 v[168:171], v78
	ds_read_b128 v[182:185], v78 offset:16
	ds_read_b128 v[186:189], v78 offset:17408
	ds_read_b128 v[118:121], v78 offset:17424
	v_add_u32_e32 v79, s92, v112
	v_lshl_add_u32 v79, v79, 11, v113
	v_add_u32_e32 v79, s24, v79
	v_lshlrev_b32_e32 v104, 1, v79
	s_waitcnt lgkmcnt(4)
	v_pk_add_f32 v[80:81], v[80:81], v[96:97]
	v_pk_add_f32 v[82:83], v[82:83], v[98:99]
	v_pk_add_f32 v[84:85], v[84:85], v[100:101]
	v_pk_add_f32 v[86:87], v[86:87], v[102:103]
	v_pk_add_f32 v[88:89], v[88:89], v[150:151]
	v_pk_add_f32 v[90:91], v[90:91], v[152:153]
	v_pk_add_f32 v[92:93], v[92:93], v[154:155]
	v_pk_add_f32 v[94:95], v[94:95], v[156:157]
	v_cvt_pk_bf16_f32 v80, v80, v81
	v_cvt_pk_bf16_f32 v81, v82, v83
	v_cvt_pk_bf16_f32 v82, v84, v85
	v_cvt_pk_bf16_f32 v83, v86, v87
	v_cvt_pk_bf16_f32 v84, v88, v89
	v_cvt_pk_bf16_f32 v85, v90, v91
	v_cvt_pk_bf16_f32 v86, v92, v93
	v_cvt_pk_bf16_f32 v87, v94, v95
	global_store_dwordx4 v104, v[80:83], s[28:29]
	global_store_dwordx4 v104, v[84:87], s[28:29] offset:16
	s_waitcnt lgkmcnt(2)
	v_lshlrev_b32_e32 v92, 16, v168
	v_and_b32_e32 v93, 0xffff0000, v168
	v_lshlrev_b32_e32 v94, 16, v169
	v_and_b32_e32 v95, 0xffff0000, v169
	v_max_f32_e64 v92, v92, v92 clamp
	v_max_f32_e64 v93, v93, v93 clamp
	v_max_f32_e64 v94, v94, v94 clamp
	v_max_f32_e64 v95, v95, v95 clamp
	v_mul_f32_e32 v92, 0x437f0000, v92
	v_mul_f32_e32 v93, 0x437f0000, v93
	v_mul_f32_e32 v94, 0x437f0000, v94
	v_mul_f32_e32 v95, 0x437f0000, v95
	v_rndne_f32_e32 v92, v92
	v_rndne_f32_e32 v93, v93
	v_rndne_f32_e32 v94, v94
	v_rndne_f32_e32 v95, v95
	v_cvt_u32_f32_e32 v92, v92
	v_cvt_u32_f32_e32 v93, v93
	v_cvt_u32_f32_sdwa v94, v94 dst_sel:WORD_1 dst_unused:UNUSED_PAD src0_sel:DWORD
	v_cvt_u32_f32_sdwa v95, v95 dst_sel:BYTE_3 dst_unused:UNUSED_PAD src0_sel:DWORD
	v_lshl_or_b32 v88, v93, 8, v92
	v_or3_b32 v88, v88, v94, v95
	v_lshlrev_b32_e32 v92, 16, v170
	v_and_b32_e32 v93, 0xffff0000, v170
	v_lshlrev_b32_e32 v94, 16, v171
	v_and_b32_e32 v95, 0xffff0000, v171
	v_max_f32_e64 v92, v92, v92 clamp
	v_max_f32_e64 v93, v93, v93 clamp
	v_max_f32_e64 v94, v94, v94 clamp
	v_max_f32_e64 v95, v95, v95 clamp
	v_mul_f32_e32 v92, 0x437f0000, v92
	v_mul_f32_e32 v93, 0x437f0000, v93
	v_mul_f32_e32 v94, 0x437f0000, v94
	v_mul_f32_e32 v95, 0x437f0000, v95
	v_rndne_f32_e32 v92, v92
	v_rndne_f32_e32 v93, v93
	v_rndne_f32_e32 v94, v94
	v_rndne_f32_e32 v95, v95
	v_cvt_u32_f32_e32 v92, v92
	v_cvt_u32_f32_e32 v93, v93
	v_cvt_u32_f32_sdwa v94, v94 dst_sel:WORD_1 dst_unused:UNUSED_PAD src0_sel:DWORD
	v_cvt_u32_f32_sdwa v95, v95 dst_sel:BYTE_3 dst_unused:UNUSED_PAD src0_sel:DWORD
	v_lshl_or_b32 v89, v93, 8, v92
	v_or3_b32 v89, v89, v94, v95
	v_lshlrev_b32_e32 v92, 16, v182
	v_and_b32_e32 v93, 0xffff0000, v182
	v_lshlrev_b32_e32 v94, 16, v183
	v_and_b32_e32 v95, 0xffff0000, v183
	v_max_f32_e64 v92, v92, v92 clamp
	v_max_f32_e64 v93, v93, v93 clamp
	v_max_f32_e64 v94, v94, v94 clamp
	v_max_f32_e64 v95, v95, v95 clamp
	v_mul_f32_e32 v92, 0x437f0000, v92
	v_mul_f32_e32 v93, 0x437f0000, v93
	v_mul_f32_e32 v94, 0x437f0000, v94
	v_mul_f32_e32 v95, 0x437f0000, v95
	v_rndne_f32_e32 v92, v92
	v_rndne_f32_e32 v93, v93
	v_rndne_f32_e32 v94, v94
	v_rndne_f32_e32 v95, v95
	v_cvt_u32_f32_e32 v92, v92
	v_cvt_u32_f32_e32 v93, v93
	v_cvt_u32_f32_sdwa v94, v94 dst_sel:WORD_1 dst_unused:UNUSED_PAD src0_sel:DWORD
	v_cvt_u32_f32_sdwa v95, v95 dst_sel:BYTE_3 dst_unused:UNUSED_PAD src0_sel:DWORD
	v_lshl_or_b32 v90, v93, 8, v92
	v_or3_b32 v90, v90, v94, v95
	v_lshlrev_b32_e32 v92, 16, v184
	v_and_b32_e32 v93, 0xffff0000, v184
	v_lshlrev_b32_e32 v94, 16, v185
	v_and_b32_e32 v95, 0xffff0000, v185
	v_max_f32_e64 v92, v92, v92 clamp
	v_max_f32_e64 v93, v93, v93 clamp
	v_max_f32_e64 v94, v94, v94 clamp
	v_max_f32_e64 v95, v95, v95 clamp
	v_mul_f32_e32 v92, 0x437f0000, v92
	v_mul_f32_e32 v93, 0x437f0000, v93
	v_mul_f32_e32 v94, 0x437f0000, v94
	v_mul_f32_e32 v95, 0x437f0000, v95
	v_rndne_f32_e32 v92, v92
	v_rndne_f32_e32 v93, v93
	v_rndne_f32_e32 v94, v94
	v_rndne_f32_e32 v95, v95
	v_cvt_u32_f32_e32 v92, v92
	v_cvt_u32_f32_e32 v93, v93
	v_cvt_u32_f32_sdwa v94, v94 dst_sel:WORD_1 dst_unused:UNUSED_PAD src0_sel:DWORD
	v_cvt_u32_f32_sdwa v95, v95 dst_sel:BYTE_3 dst_unused:UNUSED_PAD src0_sel:DWORD
	v_lshl_or_b32 v91, v93, 8, v92
	v_or3_b32 v91, v91, v94, v95
	global_store_dwordx4 v79, v[88:91], s[52:53]
	s_waitcnt lgkmcnt(0)
; __device__ void phaseA1(const Params& p) {
;     ...
;         const v2u pfv = *reinterpret_cast<const v2u*>(sm + SC_PF + ctt * 272 + cl * 2);
;         const v2u pbv = *reinterpret_cast<const v2u*>(sm + SC_PB + ctt * 272 + cl * 2);
;         *reinterpret_cast<unsigned*>(Pf8 + gi) = pk4_u8(bflo(pfv.x), bfhi(pfv.x), bflo(pfv.y), bfhi(pfv.y));
;         *reinterpret_cast<unsigned*>(Pb8 + gi) = pk4_u8(bflo(pbv.x), bfhi(pbv.x), bflo(pbv.y), bfhi(pbv.y));
;       }
;     }
;     __syncthreads();
	v_lshlrev_b32_e32 v100, 16, v186
	v_and_b32_e32 v101, 0xffff0000, v186
	v_lshlrev_b32_e32 v102, 16, v187
	v_and_b32_e32 v103, 0xffff0000, v187
	v_max_f32_e64 v100, v100, v100 clamp
	v_max_f32_e64 v101, v101, v101 clamp
	v_max_f32_e64 v102, v102, v102 clamp
	v_max_f32_e64 v103, v103, v103 clamp
	v_mul_f32_e32 v100, 0x437f0000, v100
	v_mul_f32_e32 v101, 0x437f0000, v101
	v_mul_f32_e32 v102, 0x437f0000, v102
	v_mul_f32_e32 v103, 0x437f0000, v103
	v_rndne_f32_e32 v100, v100
	v_rndne_f32_e32 v101, v101
	v_rndne_f32_e32 v102, v102
	v_rndne_f32_e32 v103, v103
	v_cvt_u32_f32_e32 v100, v100
	v_cvt_u32_f32_e32 v101, v101
	v_cvt_u32_f32_sdwa v102, v102 dst_sel:WORD_1 dst_unused:UNUSED_PAD src0_sel:DWORD
	v_cvt_u32_f32_sdwa v103, v103 dst_sel:BYTE_3 dst_unused:UNUSED_PAD src0_sel:DWORD
	v_lshl_or_b32 v96, v101, 8, v100
	v_or3_b32 v96, v96, v102, v103
	v_lshlrev_b32_e32 v100, 16, v188
	v_and_b32_e32 v101, 0xffff0000, v188
	v_lshlrev_b32_e32 v102, 16, v189
	v_and_b32_e32 v103, 0xffff0000, v189
	v_max_f32_e64 v100, v100, v100 clamp
	v_max_f32_e64 v101, v101, v101 clamp
	v_max_f32_e64 v102, v102, v102 clamp
	v_max_f32_e64 v103, v103, v103 clamp
	v_mul_f32_e32 v100, 0x437f0000, v100
	v_mul_f32_e32 v101, 0x437f0000, v101
	v_mul_f32_e32 v102, 0x437f0000, v102
	v_mul_f32_e32 v103, 0x437f0000, v103
	v_rndne_f32_e32 v100, v100
	v_rndne_f32_e32 v101, v101
	v_rndne_f32_e32 v102, v102
	v_rndne_f32_e32 v103, v103
	v_cvt_u32_f32_e32 v100, v100
	v_cvt_u32_f32_e32 v101, v101
	v_cvt_u32_f32_sdwa v102, v102 dst_sel:WORD_1 dst_unused:UNUSED_PAD src0_sel:DWORD
	v_cvt_u32_f32_sdwa v103, v103 dst_sel:BYTE_3 dst_unused:UNUSED_PAD src0_sel:DWORD
	v_lshl_or_b32 v97, v101, 8, v100
	v_or3_b32 v97, v97, v102, v103
	v_lshlrev_b32_e32 v100, 16, v118
	v_and_b32_e32 v101, 0xffff0000, v118
	v_lshlrev_b32_e32 v102, 16, v119
	v_and_b32_e32 v103, 0xffff0000, v119
	v_max_f32_e64 v100, v100, v100 clamp
	v_max_f32_e64 v101, v101, v101 clamp
	v_max_f32_e64 v102, v102, v102 clamp
	v_max_f32_e64 v103, v103, v103 clamp
	v_mul_f32_e32 v100, 0x437f0000, v100
	v_mul_f32_e32 v101, 0x437f0000, v101
	v_mul_f32_e32 v102, 0x437f0000, v102
	v_mul_f32_e32 v103, 0x437f0000, v103
	v_rndne_f32_e32 v100, v100
	v_rndne_f32_e32 v101, v101
	v_rndne_f32_e32 v102, v102
	v_rndne_f32_e32 v103, v103
	v_cvt_u32_f32_e32 v100, v100
	v_cvt_u32_f32_e32 v101, v101
	v_cvt_u32_f32_sdwa v102, v102 dst_sel:WORD_1 dst_unused:UNUSED_PAD src0_sel:DWORD
	v_cvt_u32_f32_sdwa v103, v103 dst_sel:BYTE_3 dst_unused:UNUSED_PAD src0_sel:DWORD
	v_lshl_or_b32 v98, v101, 8, v100
	v_or3_b32 v98, v98, v102, v103
	v_lshlrev_b32_e32 v100, 16, v120
	v_and_b32_e32 v101, 0xffff0000, v120
	v_lshlrev_b32_e32 v102, 16, v121
	v_and_b32_e32 v103, 0xffff0000, v121
	v_max_f32_e64 v100, v100, v100 clamp
	v_max_f32_e64 v101, v101, v101 clamp
	v_max_f32_e64 v102, v102, v102 clamp
	v_max_f32_e64 v103, v103, v103 clamp
	v_mul_f32_e32 v100, 0x437f0000, v100
	v_mul_f32_e32 v101, 0x437f0000, v101
	v_mul_f32_e32 v102, 0x437f0000, v102
	v_mul_f32_e32 v103, 0x437f0000, v103
	v_rndne_f32_e32 v100, v100
	v_rndne_f32_e32 v101, v101
	v_rndne_f32_e32 v102, v102
	v_rndne_f32_e32 v103, v103
	v_cvt_u32_f32_e32 v100, v100
	v_cvt_u32_f32_e32 v101, v101
	v_cvt_u32_f32_sdwa v102, v102 dst_sel:WORD_1 dst_unused:UNUSED_PAD src0_sel:DWORD
	v_cvt_u32_f32_sdwa v103, v103 dst_sel:BYTE_3 dst_unused:UNUSED_PAD src0_sel:DWORD
	v_lshl_or_b32 v99, v101, 8, v100
	v_or3_b32 v99, v99, v102, v103
	global_store_dwordx4 v79, v[96:99], s[46:47]
	v_lshlrev_b32_e32 v126, 2, v194
	v_and_b32_e32 v126, 28, v126
	s_add_i32 s63, s63, s65
	s_andn2_b64 vcc, exec, s[72:73]
	s_add_i32 s67, s67, s71
	s_barrier
	s_cbranch_vccz .LBB0_469

; __device__ void phaseA1(const Params& p) {
;     ...
;     #pragma unroll
;     for (int i = 0; i < 3; ++i) {
;       const int chunk = tid + 512 * i;
;       if (chunk < 67 * 16) {
;         const int pos = pos0 + (chunk >> 4) - 2;
;         v4u val = pr[i];
;         if (pos < 0 || pos >= S) val = v4u{0u, 0u, 0u, 0u};
;         *reinterpret_cast<v4u*>(sm + SC_XR + (chunk >> 4) * 272 + (chunk & 15) * 16) = val;
;       }
;     }
.LBB0_446:
	v_add_u32_e32 v76, s24, v202
	v_cmp_lt_u32_e32 vcc, s83, v76
	s_waitcnt vmcnt(6)
	s_nop 0
	v_cndmask_b32_e32 v79, 0, v11, vcc
	v_cndmask_b32_e32 v78, 0, v10, vcc
	v_cndmask_b32_e32 v77, 0, v9, vcc
	v_cndmask_b32_e32 v76, 0, v8, vcc
	ds_write_b128 v227, v[76:79] offset:51200

.LBB0_451:
	s_waitcnt vmcnt(8)
	v_add_u32_e32 v8, s25, v202
	v_med3_i32 v8, v8, 2, v238
	v_add_u32_e32 v8, s24, v8
	v_ashrrev_i32_e32 v9, 31, v8
	v_lshlrev_b64 v[8:9], 12, v[8:9]
	v_lshl_add_u64 v[8:9], v[76:77], 0, v[8:9]
	global_load_dwordx4 v[8:11], v[8:9], off

; __device__ void phaseA1(const Params& p) {
;     ...
;     #pragma unroll
;     for (int i = 0; i < 3; ++i) {
;       const int chunk = tid + 512 * i;
;       if (chunk < 67 * 16) {
;         const int pos = pos0 + (chunk >> 4) - 2;
;         v4u val = pr[i];
;         if (pos < 0 || pos >= S) val = v4u{0u, 0u, 0u, 0u};
;         *reinterpret_cast<v4u*>(sm + SC_XR + (chunk >> 4) * 272 + (chunk & 15) * 16) = val;
;       }
;     }
.LBB0_462:
	v_add_u32_e32 v76, s24, v200
	v_cmp_lt_u32_e32 vcc, s83, v76
	s_waitcnt vmcnt(7)
	s_nop 0
	v_cndmask_b32_e32 v79, 0, v3, vcc
	v_cndmask_b32_e32 v78, 0, v2, vcc
	v_cndmask_b32_e32 v77, 0, v1, vcc
	v_cndmask_b32_e32 v76, 0, v0, vcc
	ds_write_b128 v225, v[76:79] offset:51200
	s_or_b64 exec, exec, s[72:73]
	s_and_saveexec_b64 s[72:73], s[20:21]
	s_cbranch_execz .LBB0_445
.LBB0_463:
	v_add_u32_e32 v76, s24, v201
	v_cmp_lt_u32_e32 vcc, s83, v76
	s_waitcnt vmcnt(6)
	s_nop 0
	v_cndmask_b32_e32 v79, 0, v7, vcc
	v_cndmask_b32_e32 v78, 0, v6, vcc
	v_cndmask_b32_e32 v77, 0, v5, vcc
	v_cndmask_b32_e32 v76, 0, v4, vcc
	ds_write_b128 v226, v[76:79] offset:51200
	s_or_b64 exec, exec, s[72:73]
	s_and_saveexec_b64 s[72:73], s[22:23]
	s_cbranch_execnz .LBB0_446
	s_branch .LBB0_447

.LBB0_467:
	s_waitcnt vmcnt(6)
	v_add_u32_e32 v0, s25, v200
	v_med3_i32 v0, v0, 2, v238
	v_add_u32_e32 v0, s24, v0
	v_ashrrev_i32_e32 v1, 31, v0
	v_lshlrev_b64 v[0:1], 12, v[0:1]
	v_lshl_add_u64 v[0:1], v[76:77], 0, v[0:1]
	global_load_dwordx4 v[0:3], v[0:1], off
	s_or_b64 exec, exec, s[78:79]
	s_and_saveexec_b64 s[78:79], s[20:21]
	s_cbranch_execz .LBB0_450
.LBB0_468:
	s_waitcnt vmcnt(7)
	v_add_u32_e32 v4, s25, v201
	v_med3_i32 v4, v4, 2, v238
	v_add_u32_e32 v4, s24, v4
	v_ashrrev_i32_e32 v5, 31, v4
	v_lshlrev_b64 v[4:5], 12, v[4:5]
	v_lshl_add_u64 v[4:5], v[76:77], 0, v[4:5]
	global_load_dwordx4 v[4:7], v[4:5], off
	s_or_b64 exec, exec, s[78:79]
	s_and_saveexec_b64 s[78:79], s[22:23]
	s_cbranch_execnz .LBB0_451
	s_branch .LBB0_452
